# p0
# baseline (speedup 1.0000x reference)
; DEVI void phase0(const Params& p, char* shm) {
;     ...
;   for (int t = blockIdx.x; t < 8192; t += gridDim.x) {
;     const float* x = p.in[0];
;     unsigned char* xb8 = (unsigned char*)(p.ws + OFF_HB8);
;     size_t base = (size_t)t * 4096 + tid * 8;
;     float4 a = *reinterpret_cast<const float4*>(x + base);
;     float4 b = *reinterpret_cast<const float4*>(x + base + 4);
;     uint2 o;
;     o.x = pack4_fp8(a.x, a.y, a.z, a.w); o.y = pack4_fp8(b.x, b.y, b.z, b.w);
;     *reinterpret_cast<uint2*>(xb8 + base) = o;
;   }
.Lcv_chk4:
	s_mul_i32 s3, s78, 3
	s_add_i32 s3, s3, s2
	s_cmpk_gt_i32 s3, 0x1fff
	s_cbranch_scc1 .LBB0_333
	s_mov_b32 vcc_lo, s2
	s_ashr_i32 vcc_hi, vcc_lo, 31
	s_lshl_b64 s[4:5], vcc, 12
	v_lshl_add_u64 v[48:49], s[4:5], 0, v[0:1]
	v_lshl_add_u64 v[56:57], v[48:49], 2, s[36:37]
	global_load_dwordx4 v[16:19], v[56:57], off
	global_load_dwordx4 v[20:23], v[56:57], off offset:16
	s_add_i32 vcc_lo, vcc_lo, s78
	s_ashr_i32 vcc_hi, vcc_lo, 31
	s_lshl_b64 s[4:5], vcc, 12
	v_lshl_add_u64 v[50:51], s[4:5], 0, v[0:1]
	v_lshl_add_u64 v[56:57], v[50:51], 2, s[36:37]
	global_load_dwordx4 v[24:27], v[56:57], off
	global_load_dwordx4 v[28:31], v[56:57], off offset:16
	s_add_i32 vcc_lo, vcc_lo, s78
	s_ashr_i32 vcc_hi, vcc_lo, 31
	s_lshl_b64 s[4:5], vcc, 12
	v_lshl_add_u64 v[52:53], s[4:5], 0, v[0:1]
	v_lshl_add_u64 v[56:57], v[52:53], 2, s[36:37]
	global_load_dwordx4 v[32:35], v[56:57], off
	global_load_dwordx4 v[36:39], v[56:57], off offset:16
	s_add_i32 vcc_lo, vcc_lo, s78
	s_ashr_i32 vcc_hi, vcc_lo, 31
	s_lshl_b64 s[4:5], vcc, 12
	v_lshl_add_u64 v[54:55], s[4:5], 0, v[0:1]
	v_lshl_add_u64 v[56:57], v[54:55], 2, s[36:37]
	global_load_dwordx4 v[40:43], v[56:57], off
	global_load_dwordx4 v[44:47], v[56:57], off offset:16
	s_add_i32 vcc_lo, vcc_lo, s78
	s_mov_b32 s2, vcc_lo
	v_mov_b32_e32 v58, 0
	v_mov_b32_e32 v59, 0
	s_waitcnt vmcnt(6)
	v_cvt_pk_fp8_f32 v58, v16, v17
	v_cvt_pk_fp8_f32 v59, v20, v21
	v_cvt_pk_fp8_f32 v58, v18, v19 op_sel:[0,0,1]
	v_cvt_pk_fp8_f32 v59, v22, v23 op_sel:[0,0,1]
	v_mov_b32_e32 v60, 0
	v_mov_b32_e32 v61, 0
	s_waitcnt vmcnt(4)
	v_cvt_pk_fp8_f32 v60, v24, v25
	v_cvt_pk_fp8_f32 v61, v28, v29
	v_cvt_pk_fp8_f32 v60, v26, v27 op_sel:[0,0,1]
	v_cvt_pk_fp8_f32 v61, v30, v31 op_sel:[0,0,1]
	v_mov_b32_e32 v62, 0
	v_mov_b32_e32 v63, 0
	s_waitcnt vmcnt(2)
	v_cvt_pk_fp8_f32 v62, v32, v33
	v_cvt_pk_fp8_f32 v63, v36, v37
	v_cvt_pk_fp8_f32 v62, v34, v35 op_sel:[0,0,1]
	v_cvt_pk_fp8_f32 v63, v38, v39 op_sel:[0,0,1]
	v_mov_b32_e32 v64, 0
	v_mov_b32_e32 v65, 0
	s_waitcnt vmcnt(0)
	v_cvt_pk_fp8_f32 v64, v40, v41
	v_cvt_pk_fp8_f32 v65, v44, v45
	v_cvt_pk_fp8_f32 v64, v42, v43 op_sel:[0,0,1]
	v_cvt_pk_fp8_f32 v65, v46, v47 op_sel:[0,0,1]
	v_lshl_add_u64 v[48:49], s[0:1], 0, v[48:49]
	global_store_dwordx2 v[48:49], v[58:59], off
	v_lshl_add_u64 v[50:51], s[0:1], 0, v[50:51]
	global_store_dwordx2 v[50:51], v[60:61], off
	v_lshl_add_u64 v[52:53], s[0:1], 0, v[52:53]
	global_store_dwordx2 v[52:53], v[62:63], off
	v_lshl_add_u64 v[54:55], s[0:1], 0, v[54:55]
	global_store_dwordx2 v[54:55], v[64:65], off
	s_cmpk_gt_i32 s2, 0x1fff
	s_cbranch_scc0 .Lcv_chk4
	s_branch .LBB0_334

; DEVI f32x4 mfma16(bf16x8 a, bf16x8 b, f32x4 c) { return __builtin_amdgcn_mfma_f32_16x16x32_bf16(a, b, c, 0, 0, 0); }
; template <int DQK, int NQ, int MODE, int CH> ...
;     ...
;   __syncthreads();
;   LOAD_CHUNK(kt_lo);
;   STORE_CHUNK(0);
;   __syncthreads();
;   int buf = 0;
;   for (int kt0 = kt_lo; kt0 < kt_hi; kt0 += CH) {
;     if (kt0 + CH < kt_hi) LOAD_CHUNK(kt0 + CH);
; #pragma unroll
;     for (int sub = 0; sub < CH; ++sub) {
;       const int kt = kt0 + sub;
;       const u16* Ks = Ksb + buf * KBUF + sub * KTILE;
;       const u16* Vs = Vsb + buf * VBUF + sub * VTILE;
;       const int kpos = kbase + kt * 64;
;       bool active = (kt < kt_hi);
;       if (MODE == 0) {
;         int q0w = qpos0 + w * 16 * NQ;
;         active = active && (kpos + 63 >= q0w - 128) && (kpos <= q0w + 16 * NQ - 1 + 128);
;       } else if (MODE == 2) {
;         int krow = rs0 + kt;
;         active = active && (krow >= rsq) && (krow < rsq + 8);
;       }
;       if (active) {
;         f32x4 s[4][NQ];
;         __builtin_amdgcn_s_setprio(1);
; #pragma unroll
;         for (int mk = 0; mk < 4; ++mk) {
;           if (MODE == 2 && (mk < mk_lo || mk > mk_hi)) {
; #pragma unroll
;             for (int nq = 0; nq < NQ; ++nq) s[mk][nq] = f32x4{NEGBIG, NEGBIG, NEGBIG, NEGBIG};
;           } else {
;             bf16x8 kf[KS];
; #pragma unroll
;             for (int ks = 0; ks < KS; ++ks) kf[ks] = *reinterpret_cast<const bf16x8*>(Ks + (mk * 16 + fr) * KSTR + ks * 32 + fq * 8);
; #pragma unroll
;             for (int nq = 0; nq < NQ; ++nq) {
;               f32x4 a = f32x4{0.f, 0.f, 0.f, 0.f};
; #pragma unroll
;               for (int ks = 0; ks < KS; ++ks) a = mfma16(kf[ks], qf[nq][ks], a);
;               s[mk][nq] = a;
;             }
;           }
;         }
.LBB0_826:
	s_or_b64 exec, exec, s[34:35]
	s_movk_i32 s30, 0x68
	v_mul_lo_u32 v2, v50, s30
	v_lshlrev_b32_e32 v1, 3, v48
	v_lshlrev_b32_e32 v124, 1, v2
	v_lshlrev_b32_e32 v125, 1, v40
	v_add3_u32 v2, 0, v124, v125
	s_movk_i32 s30, 0x90
	v_and_b32_e32 v1, 32, v1
	s_waitcnt vmcnt(1)
	ds_write_b128 v2, v[36:39]
	v_mul_lo_u32 v2, v46, s30
	v_lshlrev_b32_e32 v1, 1, v1
	v_add3_u32 v1, 0, v2, v1
	v_lshlrev_b32_e32 v2, 2, v48
	v_lshlrev_b32_e32 v3, 5, v48
	v_and_b32_e32 v2, 8, v2
	v_and_b32_e32 v3, 32, v3
	v_add3_u32 v126, v1, v2, v3
	v_add_u32_e32 v1, 0x6800, v126
	v_lshlrev_b32_e32 v127, 4, v51
	s_waitcnt vmcnt(0)
	ds_write2_b64 v1, v[32:33], v[34:35] offset1:2
	s_and_saveexec_b64 s[30:31], s[2:3]
	s_xor_b64 s[2:3], exec, s[30:31]
	v_lshlrev_b32_e32 v127, 4, v51
	s_or_saveexec_b64 s[2:3], s[2:3]
	s_movk_i32 s30, 0xd0
	v_mul_lo_u32 v128, v47, s30
	s_xor_b64 exec, exec, s[2:3]
	v_add3_u32 v1, 0, v128, v127
	ds_write_b128 v1, v[28:31]
	s_or_b64 exec, exec, s[2:3]
	v_mov_b64_e32 v[2:3], s[28:29]
	v_mad_i64_i32 v[2:3], s[2:3], v47, s79, v[2:3]
	v_mad_i64_i32 v[32:33], s[2:3], v50, s79, 0
	v_mad_u64_u32 v[2:3], s[2:3], s0, v122, v[2:3]
	s_add_i32 s2, s21, s0
	s_ashr_i32 s3, s2, 31
	s_lshl_b64 s[2:3], s[2:3], 19
	v_and_b32_e32 v36, 7, v48
	v_lshl_add_u64 v[32:33], s[28:29], 0, v[32:33]
	v_lshl_add_u64 v[34:35], s[2:3], 0, v[42:43]
	v_lshlrev_b32_e32 v36, 4, v36
	v_mov_b32_e32 v37, v0
	v_mad_u64_u32 v[32:33], s[2:3], s0, v122, v[32:33]
	v_lshl_add_u64 v[2:3], v[44:45], 1, v[2:3]
	v_lshl_add_u64 v[34:35], v[34:35], 0, v[36:37]
	v_lshl_add_u64 v[32:33], v[40:41], 1, v[32:33]
	v_mov_b32_e32 v44, 0
	v_ashrrev_i32_e32 v75, 31, v74
	v_ashrrev_i32_e32 v73, 31, v72
	v_lshl_add_u32 v1, v89, 4, 0
	v_mul_u32_u24_e32 v129, 0xd0, v49
	v_mul_u32_u24_e32 v123, 0x90, v49
	v_lshl_add_u64 v[2:3], s[24:25], 0, v[2:3]
	v_lshl_add_u64 v[78:79], s[14:15], 0, v[34:35]
	v_lshl_add_u64 v[80:81], s[24:25], 0, v[32:33]
	v_mov_b32_e32 v82, 0xf149f2ca
	s_mov_b32 s30, 0
	s_mov_b64 s[2:3], 0
	v_mov_b32_e32 v45, v44
	v_mov_b32_e32 v46, v44
	v_mov_b32_e32 v47, v44
	v_mov_b32_e32 v60, v44
	v_mov_b32_e32 v61, v44
	v_mov_b32_e32 v62, v44
	v_mov_b32_e32 v63, v44
	v_mov_b32_e32 v36, v44
	v_mov_b32_e32 v37, v44
	v_mov_b32_e32 v38, v44
	v_mov_b32_e32 v39, v44
	v_mov_b32_e32 v52, v44
	v_mov_b32_e32 v53, v44
	v_mov_b32_e32 v54, v44
	v_mov_b32_e32 v55, v44
	v_mov_b32_e32 v40, v44
	v_mov_b32_e32 v41, v44
	v_mov_b32_e32 v42, v44
	v_mov_b32_e32 v43, v44
	v_mov_b32_e32 v56, v44
	v_mov_b32_e32 v57, v44
	v_mov_b32_e32 v58, v44
	v_mov_b32_e32 v59, v44
	v_mov_b32_e32 v32, v44
	v_mov_b32_e32 v33, v44
	v_mov_b32_e32 v34, v44
	v_mov_b32_e32 v35, v44
	v_mov_b32_e32 v48, v44
	v_mov_b32_e32 v49, v44
	v_mov_b32_e32 v50, v44
	v_mov_b32_e32 v51, v44
	v_mov_b32_e32 v76, v44
	v_mov_b32_e32 v77, v44
	v_mov_b32_e32 v83, 0xf149f2ca
	s_waitcnt lgkmcnt(0)
	s_barrier
	v_lshl_add_u64 v[64:65], v[80:81], 0, s[2:3]
	global_load_dwordx4 v[68:71], v[64:65], off
	s_nop 0
	global_load_dwordx4 v[64:67], v[78:79], off
	s_and_saveexec_b64 s[28:29], vcc
	v_lshl_add_u64 v[28:29], v[2:3], 0, s[2:3]
	global_load_dwordx4 v[28:31], v[28:29], off
	s_or_b64 exec, exec, s[28:29]
	s_mov_b64 s[28:29], 0x18000
	v_lshl_add_u64 v[80:81], v[80:81], 0, s[28:29]
	v_lshl_add_u64 v[2:3], v[2:3], 0, s[28:29]
	s_mov_b64 s[28:29], 0x80
	v_lshl_add_u64 v[78:79], v[78:79], 0, s[28:29]
.LBB0_831:
	s_xor_b32 s21, s30, 1
	s_mul_i32 s28, s21, 0x2400
	s_mul_i32 s21, s21, 0x3400
	v_add3_u32 v212, s21, v124, v125
	s_waitcnt vmcnt(1)
	ds_write_b128 v212, v[68:71]
	v_add_u32_e32 v213, s28, v126
	v_add_u32_e32 v213, 0x6800, v213
	s_waitcnt vmcnt(0)
	ds_write2_b64 v213, v[64:65], v[66:67] offset1:2
	s_and_saveexec_b64 s[28:29], vcc
	v_add3_u32 v240, s21, v128, v127
	ds_write_b128 v240, v[28:31]
	s_or_b64 exec, exec, s[28:29]
	v_lshl_add_u64 v[64:65], v[80:81], 0, s[2:3]
	global_load_dwordx4 v[68:71], v[64:65], off
	s_nop 0
	global_load_dwordx4 v[64:67], v[78:79], off
	s_and_saveexec_b64 s[28:29], vcc
	s_cbranch_execz .LBB0_833
	v_lshl_add_u64 v[28:29], v[2:3], 0, s[2:3]
	global_load_dwordx4 v[28:31], v[28:29], off
.LBB0_833:
	s_or_b64 exec, exec, s[28:29]
	s_mul_i32 s21, s30, 0x3400
	s_mul_i32 s28, s30, 0x2400
	v_add3_u32 v210, v1, s21, v129
	v_add3_u32 v211, v1, s28, v123
	ds_read_b128 v[162:165], v210 offset:0
	ds_read_b128 v[166:169], v210 offset:64
	ds_read_b128 v[170:173], v210 offset:128
	ds_read_b128 v[174:177], v210 offset:3328
	ds_read_b128 v[178:181], v210 offset:3392
	ds_read_b128 v[182:185], v210 offset:3456
	ds_read_b128 v[186:189], v210 offset:6656
	ds_read_b128 v[190:193], v210 offset:6720
	ds_read_b128 v[194:197], v210 offset:6784
	ds_read_b128 v[198:201], v210 offset:9984
	ds_read_b128 v[202:205], v210 offset:10048
	ds_read_b128 v[206:209], v210 offset:10112
	s_waitcnt lgkmcnt(9)
	v_mfma_f32_16x16x32_bf16 v[90:93], v[162:165], v[24:27], 0
	v_mfma_f32_16x16x32_bf16 v[90:93], v[166:169], v[20:23], v[90:93]
	v_mfma_f32_16x16x32_bf16 v[90:93], v[170:173], v[4:7], v[90:93]
	s_waitcnt lgkmcnt(6)
	v_mfma_f32_16x16x32_bf16 v[94:97], v[174:177], v[24:27], 0
	v_mfma_f32_16x16x32_bf16 v[94:97], v[178:181], v[20:23], v[94:97]
	v_mfma_f32_16x16x32_bf16 v[94:97], v[182:185], v[4:7], v[94:97]
	s_waitcnt lgkmcnt(3)
	v_mfma_f32_16x16x32_bf16 v[98:101], v[186:189], v[24:27], 0
	v_mfma_f32_16x16x32_bf16 v[98:101], v[190:193], v[20:23], v[98:101]
	v_mfma_f32_16x16x32_bf16 v[98:101], v[194:197], v[4:7], v[98:101]
	s_waitcnt lgkmcnt(0)
; template <int DQK, int NQ, int MODE, int CH> ...
;     ...
; #pragma unroll
;         for (int nq = 0; nq < NQ; ++nq) {
;           float mx = NEGBIG;
;           if (MODE == 1) {
; #pragma unroll
;             for (int mk = 0; mk < 4; ++mk)
; #pragma unroll
;               for (int j = 0; j < 4; ++j) mx = fmaxf(mx, s[mk][nq][j]);
;             mx *= sc2;
;           } else {
; #pragma unroll
;             for (int mk = 0; mk < 4; ++mk) {
;               if (MODE == 2 && (mk < mk_lo || mk > mk_hi)) continue;
; #pragma unroll
;               for (int j = 0; j < 4; ++j) {
;                 float v;
;                 if (MODE == 0) {
;                   int qp = qpos0 + w * 16 * NQ + nq * 16 + fr;
;                   int kp = kpos + mk * 16 + fq * 4 + j;
;                   int dist = qp > kp ? qp - kp : kp - qp;
;                   v = s[mk][nq][j] * sc2 - slope2 * (float)dist;
;                   if (dist > 128) v = NEGBIG;
;                 } else {
;                   const float* brow = bias_s + (rs0 + kt - rq + 7) * 31;
;                   v = __builtin_fmaf(s[mk][nq][j], sc2, brow[dci[nq][mk][j]]) + pen[nq][mk][j];
;                 }
;                 s[mk][nq][j] = v;
;                 mx = fmaxf(mx, v);
;               }
;             }
;           }
;           mx = xor16_max(mx);
;           mx = xor32_max(mx);
;           float mnew = fmaxf(mrun[nq], mx);
;           float alpha = __builtin_amdgcn_exp2f(mrun[nq] - mnew);
;           mrun[nq] = mnew;
;           float ps = 0.f;
; #pragma unroll
;           for (int mk = 0; mk < 4; ++mk) {
;             if (MODE == 2 && (mk < mk_lo || mk > mk_hi)) {
;               s[mk][nq] = f32x4{0.f, 0.f, 0.f, 0.f};
;               continue;
;             }
; #pragma unroll
;             for (int j = 0; j < 4; ++j) {
;               float pv;
;               if (MODE == 1) pv = __builtin_amdgcn_exp2f(__builtin_fmaf(s[mk][nq][j], sc2, -mnew));
;               else pv = __builtin_amdgcn_exp2f(s[mk][nq][j] - mnew);
;               s[mk][nq][j] = pv;
;               ps += pv;
;             }
;           }
;           lsum[nq] = lsum[nq] * alpha + ps;
; #pragma unroll
;           for (int md = 0; md < 4; ++md) {
;             o[md][nq][0] *= alpha; o[md][nq][1] *= alpha; o[md][nq][2] *= alpha; o[md][nq][3] *= alpha;
;           }
;         }
;         __builtin_amdgcn_s_setprio(1);
; #pragma unroll
	v_mfma_f32_16x16x32_bf16 v[102:105], v[198:201], v[24:27], 0
	v_mfma_f32_16x16x32_bf16 v[102:105], v[202:205], v[20:23], v[102:105]
	v_mfma_f32_16x16x32_bf16 v[102:105], v[206:209], v[4:7], v[102:105]
	ds_read_b128 v[216:219], v211 offset:26624
	ds_read_b128 v[220:223], v211 offset:28928
	ds_read_b128 v[224:227], v211 offset:31232
	ds_read_b128 v[228:231], v211 offset:33536
	ds_read_b128 v[232:235], v211 offset:26688
	ds_read_b128 v[236:239], v211 offset:28992
	ds_read_b128 v[244:247], v211 offset:31296
	ds_read_b128 v[248:251], v211 offset:33600
	v_mfma_f32_16x16x32_bf16 v[106:109], v[162:165], v[8:11], 0
	v_mfma_f32_16x16x32_bf16 v[106:109], v[166:169], v[12:15], v[106:109]
	v_max3_f32 v84, v90, v91, v92
	v_max3_f32 v84, v84, v93, v94
	v_max3_f32 v84, v84, v95, v96
	v_max3_f32 v84, v84, v97, v98
	v_max3_f32 v84, v84, v99, v100
	v_max3_f32 v84, v84, v101, v102
	v_max3_f32 v84, v84, v103, v104
	v_max_f32_e32 v84, v84, v105
	v_mfma_f32_16x16x32_bf16 v[106:109], v[170:173], v[16:19], v[106:109]
	v_mul_f32_e32 v84, 0x3e16c740, v84
	v_mov_b32_e32 v85, v84
	s_nop 1
	v_permlane16_swap_b32_e32 v84, v85
	v_max_f32_e32 v84, v84, v85
	v_mov_b32_e32 v85, v84
	s_nop 1
	v_permlane32_swap_b32_e32 v84, v85
	v_max3_f32 v130, v82, v84, v85
	v_sub_f32_e32 v86, v82, v130
	v_exp_f32_e32 v86, v86
	v_fma_f32 v90, v90, s80, -v130
	v_mfma_f32_16x16x32_bf16 v[110:113], v[174:177], v[8:11], 0
	v_exp_f32_e32 v90, v90
	v_mul_f32_e32 v48, v86, v48
	v_fma_f32 v91, v91, s80, -v130
	v_exp_f32_e32 v91, v91
	v_mul_f32_e32 v49, v86, v49
	v_fma_f32 v92, v92, s80, -v130
	v_exp_f32_e32 v92, v92
	v_mul_f32_e32 v50, v86, v50
	v_mfma_f32_16x16x32_bf16 v[110:113], v[178:181], v[12:15], v[110:113]
	v_add_f32_e32 v136, v90, v91
	v_fma_f32 v93, v93, s80, -v130
	v_exp_f32_e32 v93, v93
	v_mul_f32_e32 v51, v86, v51
	v_add_f32_e32 v136, v136, v92
	v_fma_f32 v94, v94, s80, -v130
	v_exp_f32_e32 v94, v94
	v_mul_f32_e32 v52, v86, v52
	v_mfma_f32_16x16x32_bf16 v[110:113], v[182:185], v[16:19], v[110:113]
	v_add_f32_e32 v136, v136, v93
	v_fma_f32 v95, v95, s80, -v130
	v_exp_f32_e32 v95, v95
	v_mul_f32_e32 v53, v86, v53
	v_add_f32_e32 v136, v136, v94
	v_fma_f32 v96, v96, s80, -v130
	v_exp_f32_e32 v96, v96
	v_mul_f32_e32 v54, v86, v54
	v_mfma_f32_16x16x32_bf16 v[114:117], v[186:189], v[8:11], 0
	v_add_f32_e32 v136, v136, v95
	v_fma_f32 v97, v97, s80, -v130
	v_exp_f32_e32 v97, v97
	v_mul_f32_e32 v55, v86, v55
	v_add_f32_e32 v136, v136, v96
	v_fma_f32 v98, v98, s80, -v130
	v_exp_f32_e32 v98, v98
	v_mfma_f32_16x16x32_bf16 v[114:117], v[190:193], v[12:15], v[114:117]
	v_mul_f32_e32 v56, v86, v56
	v_add_f32_e32 v136, v136, v97
	v_fma_f32 v99, v99, s80, -v130
	v_exp_f32_e32 v99, v99
	v_mul_f32_e32 v57, v86, v57
	v_add_f32_e32 v136, v136, v98
	v_fma_f32 v100, v100, s80, -v130
	v_exp_f32_e32 v100, v100
	v_mfma_f32_16x16x32_bf16 v[114:117], v[194:197], v[16:19], v[114:117]
	v_mul_f32_e32 v58, v86, v58
	v_add_f32_e32 v136, v136, v99
	v_fma_f32 v101, v101, s80, -v130
	v_exp_f32_e32 v101, v101
	v_mul_f32_e32 v59, v86, v59
	v_add_f32_e32 v136, v136, v100
	v_fma_f32 v102, v102, s80, -v130
	v_exp_f32_e32 v102, v102
	v_mfma_f32_16x16x32_bf16 v[132:135], v[198:201], v[8:11], 0
	v_mul_f32_e32 v60, v86, v60
	v_add_f32_e32 v136, v136, v101
	v_fma_f32 v103, v103, s80, -v130
	v_exp_f32_e32 v103, v103
	v_mul_f32_e32 v61, v86, v61
	v_add_f32_e32 v136, v136, v102
	v_fma_f32 v104, v104, s80, -v130
	v_exp_f32_e32 v104, v104
	v_mfma_f32_16x16x32_bf16 v[132:135], v[202:205], v[12:15], v[132:135]
	v_mul_f32_e32 v62, v86, v62
	v_add_f32_e32 v136, v136, v103
	v_fma_f32 v105, v105, s80, -v130
	v_exp_f32_e32 v105, v105
	v_mul_f32_e32 v63, v86, v63
	v_add_f32_e32 v136, v136, v104
	v_cvt_pk_bf16_f32 v90, v90, v91
	v_add_f32_e32 v136, v136, v105
	v_mfma_f32_16x16x32_bf16 v[132:135], v[206:209], v[16:19], v[132:135]
	v_cvt_pk_bf16_f32 v91, v92, v93
	v_fma_f32 v76, v76, v86, v136
	v_cvt_pk_bf16_f32 v92, v94, v95
	v_cvt_pk_bf16_f32 v93, v96, v97
	v_cvt_pk_bf16_f32 v98, v98, v99
	v_cvt_pk_bf16_f32 v99, v100, v101
	v_cvt_pk_bf16_f32 v100, v102, v103
	v_cvt_pk_bf16_f32 v101, v104, v105
	s_waitcnt lgkmcnt(0)
	v_max3_f32 v84, v106, v107, v108
	v_max3_f32 v84, v84, v109, v110
	v_max3_f32 v84, v84, v111, v112
	v_max3_f32 v84, v84, v113, v114
	v_max3_f32 v84, v84, v115, v116
	v_max3_f32 v84, v84, v117, v132
	v_max3_f32 v84, v84, v133, v134
	v_max_f32_e32 v84, v84, v135
	v_mul_f32_e32 v84, 0x3e16c740, v84
	v_mov_b32_e32 v85, v84
	s_nop 1
	v_permlane16_swap_b32_e32 v84, v85
	v_max_f32_e32 v84, v84, v85
	v_mfma_f32_16x16x32_bf16 v[48:51], v[216:219], v[90:93], v[48:51]
	v_mov_b32_e32 v85, v84
	s_nop 1
	v_permlane32_swap_b32_e32 v84, v85
	v_max3_f32 v131, v83, v84, v85
	v_sub_f32_e32 v87, v83, v131
	v_exp_f32_e32 v87, v87
	v_fma_f32 v106, v106, s80, -v131
	v_exp_f32_e32 v106, v106
	v_mul_f32_e32 v32, v87, v32
	v_fma_f32 v107, v107, s80, -v131
	v_exp_f32_e32 v107, v107
	v_mul_f32_e32 v33, v87, v33
	v_mfma_f32_16x16x32_bf16 v[56:59], v[220:223], v[90:93], v[56:59]
	v_fma_f32 v108, v108, s80, -v131
	v_exp_f32_e32 v108, v108
	v_mul_f32_e32 v34, v87, v34
	v_add_f32_e32 v137, v106, v107
	v_fma_f32 v109, v109, s80, -v131
	v_exp_f32_e32 v109, v109
	v_mul_f32_e32 v35, v87, v35
	v_add_f32_e32 v137, v137, v108
	v_fma_f32 v110, v110, s80, -v131
	v_mfma_f32_16x16x32_bf16 v[52:55], v[224:227], v[90:93], v[52:55]
	v_exp_f32_e32 v110, v110
	v_mul_f32_e32 v36, v87, v36
	v_add_f32_e32 v137, v137, v109
	v_fma_f32 v111, v111, s80, -v131
	v_exp_f32_e32 v111, v111
	v_mul_f32_e32 v37, v87, v37
	v_add_f32_e32 v137, v137, v110
	v_fma_f32 v112, v112, s80, -v131
	v_exp_f32_e32 v112, v112
	v_mul_f32_e32 v38, v87, v38
	v_mfma_f32_16x16x32_bf16 v[60:63], v[228:231], v[90:93], v[60:63]
; DEVI f32x4 mfma16(bf16x8 a, bf16x8 b, f32x4 c) { return __builtin_amdgcn_mfma_f32_16x16x32_bf16(a, b, c, 0, 0, 0); }
; template <int DQK, int NQ, int MODE, int CH> ...
;     ...
;         __builtin_amdgcn_s_setprio(1);
; #pragma unroll
;         for (int kc = 0; kc < 2; ++kc) {
;           if (MODE == 2 && (2 * kc + 1 < mk_lo || 2 * kc > mk_hi)) continue;
;           bf16x8 pf[NQ];
; #pragma unroll
;           for (int nq = 0; nq < NQ; ++nq) {
;             V16 t;
;             t.u.x = pack2(s[2 * kc][nq][0], s[2 * kc][nq][1]);
;             t.u.y = pack2(s[2 * kc][nq][2], s[2 * kc][nq][3]);
;             t.u.z = pack2(s[2 * kc + 1][nq][0], s[2 * kc + 1][nq][1]);
;             t.u.w = pack2(s[2 * kc + 1][nq][2], s[2 * kc + 1][nq][3]);
;             pf[nq] = t.v;
;           }
; #pragma unroll
;           for (int md = 0; md < 4; ++md) {
;             const bf16x8 vfr = *reinterpret_cast<const bf16x8*>(Vs + (md * 16 + fr) * VSTR + kc * 32 + fq * 8);
; #pragma unroll
;             for (int nq = 0; nq < NQ; ++nq) o[md][nq] = mfma16(vfr, pf[nq], o[md][nq]);
;           }
;         }
;         __builtin_amdgcn_s_setprio(0);
;       }
;     }
;     if (kt0 + CH < kt_hi) STORE_CHUNK(buf ^ 1);
;     buf ^= 1;
;     __syncthreads();
;   }
	v_add_f32_e32 v137, v137, v111
	v_fma_f32 v113, v113, s80, -v131
	v_exp_f32_e32 v113, v113
	v_mul_f32_e32 v39, v87, v39
	v_add_f32_e32 v137, v137, v112
	v_fma_f32 v114, v114, s80, -v131
	v_exp_f32_e32 v114, v114
	v_mul_f32_e32 v40, v87, v40
	v_add_f32_e32 v137, v137, v113
	v_mfma_f32_16x16x32_bf16 v[48:51], v[232:235], v[98:101], v[48:51]
	v_fma_f32 v115, v115, s80, -v131
	v_exp_f32_e32 v115, v115
	v_mul_f32_e32 v41, v87, v41
	v_add_f32_e32 v137, v137, v114
	v_fma_f32 v116, v116, s80, -v131
	v_exp_f32_e32 v116, v116
	v_mul_f32_e32 v42, v87, v42
	v_add_f32_e32 v137, v137, v115
	v_fma_f32 v117, v117, s80, -v131
	v_exp_f32_e32 v117, v117
	v_mfma_f32_16x16x32_bf16 v[56:59], v[236:239], v[98:101], v[56:59]
	v_mul_f32_e32 v43, v87, v43
	v_add_f32_e32 v137, v137, v116
	v_fma_f32 v132, v132, s80, -v131
	v_exp_f32_e32 v132, v132
	v_mul_f32_e32 v44, v87, v44
	v_add_f32_e32 v137, v137, v117
	v_fma_f32 v133, v133, s80, -v131
	v_exp_f32_e32 v133, v133
	v_mul_f32_e32 v45, v87, v45
	v_mfma_f32_16x16x32_bf16 v[52:55], v[244:247], v[98:101], v[52:55]
	v_add_f32_e32 v137, v137, v132
	v_fma_f32 v134, v134, s80, -v131
	v_exp_f32_e32 v134, v134
	v_mul_f32_e32 v46, v87, v46
	v_add_f32_e32 v137, v137, v133
	v_fma_f32 v135, v135, s80, -v131
	v_exp_f32_e32 v135, v135
	v_mul_f32_e32 v47, v87, v47
	v_add_f32_e32 v137, v137, v134
	v_cvt_pk_bf16_f32 v106, v106, v107
	v_mfma_f32_16x16x32_bf16 v[60:63], v[248:251], v[98:101], v[60:63]
	v_add_f32_e32 v137, v137, v135
	v_cvt_pk_bf16_f32 v107, v108, v109
	v_fma_f32 v77, v77, v87, v137
	v_cvt_pk_bf16_f32 v108, v110, v111
	v_cvt_pk_bf16_f32 v109, v112, v113
	v_cvt_pk_bf16_f32 v114, v114, v115
	v_cvt_pk_bf16_f32 v115, v116, v117
	v_cvt_pk_bf16_f32 v116, v132, v133
	v_cvt_pk_bf16_f32 v117, v134, v135
	s_nop 0
	v_mfma_f32_16x16x32_bf16 v[32:35], v[216:219], v[106:109], v[32:35]
	v_mfma_f32_16x16x32_bf16 v[40:43], v[220:223], v[106:109], v[40:43]
	v_mfma_f32_16x16x32_bf16 v[36:39], v[224:227], v[106:109], v[36:39]
	v_mfma_f32_16x16x32_bf16 v[44:47], v[228:231], v[106:109], v[44:47]
	v_mfma_f32_16x16x32_bf16 v[32:35], v[232:235], v[114:117], v[32:35]
	v_mfma_f32_16x16x32_bf16 v[40:43], v[236:239], v[114:117], v[40:43]
	v_mfma_f32_16x16x32_bf16 v[36:39], v[244:247], v[114:117], v[36:39]
	v_mfma_f32_16x16x32_bf16 v[44:47], v[248:251], v[114:117], v[44:47]
	s_xor_b32 s30, s30, 1
	s_add_u32 s2, s2, 0x18000
	s_addc_u32 s3, s3, 0
	s_mov_b64 s[28:29], 0x80
	s_cmp_lg_u32 s2, 0x5e8000
	v_lshl_add_u64 v[78:79], v[78:79], 0, s[28:29]
	s_waitcnt lgkmcnt(0)
	s_barrier
	s_cbranch_scc0 .LBB0_837
	v_mov_b32_e32 v82, v130
	v_mov_b32_e32 v83, v131
	s_branch .LBB0_831
.LBB0_837:
	s_waitcnt vmcnt(0)
	s_lshl_b64 s[2:3], s[4:5], 11
	s_add_u32 s2, s86, s2
	s_addc_u32 s3, s87, s3
	s_lshl_b32 s0, s0, 7
	s_add_u32 s2, s2, s0
	s_addc_u32 s3, s3, 0
	s_setprio 1
	v_add_u32_e32 v2, v1, v129
	ds_read_b128 v[28:31], v2 offset:13312
	ds_read_b128 v[68:71], v2 offset:13376
	ds_read_b128 v[78:81], v2 offset:13440
	ds_read_b128 v[82:85], v2 offset:16704
	ds_read_b128 v[90:93], v2 offset:16768
	ds_read_b128 v[98:101], v2 offset:20096
	s_waitcnt lgkmcnt(5)
	v_mfma_f32_16x16x32_bf16 v[64:67], v[28:31], v[24:27], 0
	ds_read_b128 v[94:97], v2 offset:20032
	v_mfma_f32_16x16x32_bf16 v[28:31], v[28:31], v[8:11], 0
	s_waitcnt lgkmcnt(5)
	v_mfma_f32_16x16x32_bf16 v[64:67], v[68:71], v[20:23], v[64:67]
	v_mfma_f32_16x16x32_bf16 v[28:31], v[68:71], v[12:15], v[28:31]
	ds_read_b128 v[68:71], v2 offset:16640
	s_waitcnt lgkmcnt(5)
	v_mfma_f32_16x16x32_bf16 v[64:67], v[78:81], v[4:7], v[64:67]
	v_mfma_f32_16x16x32_bf16 v[28:31], v[78:81], v[16:19], v[28:31]
	s_waitcnt lgkmcnt(0)
	v_mfma_f32_16x16x32_bf16 v[78:81], v[68:71], v[24:27], 0
	v_mfma_f32_16x16x32_bf16 v[68:71], v[68:71], v[8:11], 0
	v_mfma_f32_16x16x32_bf16 v[78:81], v[82:85], v[20:23], v[78:81]
	v_mfma_f32_16x16x32_bf16 v[68:71], v[82:85], v[12:15], v[68:71]
	ds_read_b128 v[82:85], v2 offset:19968
	v_mfma_f32_16x16x32_bf16 v[78:81], v[90:93], v[4:7], v[78:81]
	v_mfma_f32_16x16x32_bf16 v[68:71], v[90:93], v[16:19], v[68:71]
	s_waitcnt lgkmcnt(0)
	v_mfma_f32_16x16x32_bf16 v[90:93], v[82:85], v[24:27], 0
	v_mfma_f32_16x16x32_bf16 v[82:85], v[82:85], v[8:11], 0
	v_mfma_f32_16x16x32_bf16 v[90:93], v[94:97], v[20:23], v[90:93]
	v_mfma_f32_16x16x32_bf16 v[82:85], v[94:97], v[12:15], v[82:85]
	ds_read_b128 v[94:97], v2 offset:23296
	v_mfma_f32_16x16x32_bf16 v[90:93], v[98:101], v[4:7], v[90:93]
	v_mfma_f32_16x16x32_bf16 v[82:85], v[98:101], v[16:19], v[82:85]
	ds_read_b128 v[98:101], v2 offset:23360
	s_waitcnt lgkmcnt(1)
	v_mfma_f32_16x16x32_bf16 v[24:27], v[94:97], v[24:27], 0
	s_waitcnt lgkmcnt(0)
	v_mfma_f32_16x16x32_bf16 v[20:23], v[98:101], v[20:23], v[24:27]
	s_nop 5
	ds_read_b128 v[24:27], v2 offset:23424
	s_waitcnt lgkmcnt(0)
; template <int DQK, int NQ, int MODE, int CH> ...
;     ...
; #pragma unroll
;         for (int nq = 0; nq < NQ; ++nq) {
;           float mx = NEGBIG;
;           if (MODE == 1) {
; #pragma unroll
;             for (int mk = 0; mk < 4; ++mk)
; #pragma unroll
;               for (int j = 0; j < 4; ++j) mx = fmaxf(mx, s[mk][nq][j]);
;             mx *= sc2;
;           } else {
; #pragma unroll
;             for (int mk = 0; mk < 4; ++mk) {
;               if (MODE == 2 && (mk < mk_lo || mk > mk_hi)) continue;
; #pragma unroll
;               for (int j = 0; j < 4; ++j) {
;                 float v;
;                 if (MODE == 0) {
;                   int qp = qpos0 + w * 16 * NQ + nq * 16 + fr;
;                   int kp = kpos + mk * 16 + fq * 4 + j;
;                   int dist = qp > kp ? qp - kp : kp - qp;
;                   v = s[mk][nq][j] * sc2 - slope2 * (float)dist;
;                   if (dist > 128) v = NEGBIG;
;                 } else {
;                   const float* brow = bias_s + (rs0 + kt - rq + 7) * 31;
;                   v = __builtin_fmaf(s[mk][nq][j], sc2, brow[dci[nq][mk][j]]) + pen[nq][mk][j];
;                 }
;                 s[mk][nq][j] = v;
;                 mx = fmaxf(mx, v);
;               }
;             }
;           }
;           mx = xor16_max(mx);
;           mx = xor32_max(mx);
;           float mnew = fmaxf(mrun[nq], mx);
;           float alpha = __builtin_amdgcn_exp2f(mrun[nq] - mnew);
;           mrun[nq] = mnew;
;           float ps = 0.f;
; #pragma unroll
;           for (int mk = 0; mk < 4; ++mk) {
;             if (MODE == 2 && (mk < mk_lo || mk > mk_hi)) {
;               s[mk][nq] = f32x4{0.f, 0.f, 0.f, 0.f};
;               continue;
;             }
; #pragma unroll
;             for (int j = 0; j < 4; ++j) {
;               float pv;
;               if (MODE == 1) pv = __builtin_amdgcn_exp2f(__builtin_fmaf(s[mk][nq][j], sc2, -mnew));
;               else pv = __builtin_amdgcn_exp2f(s[mk][nq][j] - mnew);
;               s[mk][nq][j] = pv;
;               ps += pv;
;             }
;           }
;           lsum[nq] = lsum[nq] * alpha + ps;
; #pragma unroll
;           for (int md = 0; md < 4; ++md) {
;             o[md][nq][0] *= alpha; o[md][nq][1] *= alpha; o[md][nq][2] *= alpha; o[md][nq][3] *= alpha;
;           }
;         }
;         __builtin_amdgcn_s_setprio(1);
; #pragma unroll
	v_mfma_f32_16x16x32_bf16 v[2:5], v[24:27], v[4:7], v[20:23]
	v_mfma_f32_16x16x32_bf16 v[6:9], v[94:97], v[8:11], 0
	v_mfma_f32_16x16x32_bf16 v[6:9], v[98:101], v[12:15], v[6:9]
	v_mfma_f32_16x16x32_bf16 v[6:9], v[24:27], v[16:19], v[6:9]
	s_setprio 0
	v_max3_f32 v10, v64, s77, v65
	v_max3_f32 v10, v10, v66, v67
	v_max3_f32 v10, v10, v78, v79
	v_max3_f32 v10, v10, v80, v81
	v_max3_f32 v10, v10, v90, v91
	v_max3_f32 v10, v10, v92, v93
	v_max3_f32 v10, v10, v2, v3
	v_max3_f32 v10, v10, v4, v5
	v_mul_f32_e32 v10, 0x3e16c740, v10
	v_mov_b32_e32 v11, v10
	s_nop 1
	v_permlane16_swap_b32_e32 v10, v11
	v_max3_f32 v16, v28, s77, v29
	v_max_f32_e32 v11, v11, v11
	v_max_f32_e32 v10, v10, v10
	v_max3_f32 v16, v16, v30, v31
	v_max_f32_e32 v10, v10, v11
	v_max3_f32 v16, v16, v68, v69
	v_mov_b32_e32 v11, v10
	v_max3_f32 v16, v16, v70, v71
	s_nop 0
	v_permlane32_swap_b32_e32 v10, v11
	v_max3_f32 v16, v16, v82, v83
	v_max3_f32 v10, v130, v10, v11
	v_max3_f32 v16, v16, v84, v85
	v_sub_f32_e32 v11, v130, v10
	v_max3_f32 v16, v16, v6, v7
	v_exp_f32_e32 v14, v11
	v_fma_f32 v11, v64, s80, -v10
	v_max3_f32 v16, v16, v8, v9
	v_exp_f32_e32 v15, v11
	v_fma_f32 v11, v65, s80, -v10
	v_mul_f32_e32 v16, 0x3e16c740, v16
	v_exp_f32_e32 v17, v11
	v_fma_f32 v11, v66, s80, -v10
	v_mov_b32_e32 v26, v16
	v_exp_f32_e32 v64, v11
	v_fma_f32 v11, v67, s80, -v10
	v_permlane16_swap_b32_e32 v16, v26
	v_exp_f32_e32 v65, v11
	v_fma_f32 v11, v78, s80, -v10
	v_max_f32_e32 v26, v26, v26
	v_max_f32_e32 v16, v16, v16
	v_exp_f32_e32 v66, v11
	v_fma_f32 v11, v79, s80, -v10
	v_max_f32_e32 v16, v16, v26
	v_exp_f32_e32 v67, v11
	v_fma_f32 v11, v80, s80, -v10
	v_mov_b32_e32 v26, v16
	v_exp_f32_e32 v78, v11
	v_fma_f32 v11, v81, s80, -v10
	v_permlane32_swap_b32_e32 v16, v26
	v_exp_f32_e32 v79, v11
	v_fma_f32 v11, v90, s80, -v10
	v_max3_f32 v26, v131, v16, v26
	v_exp_f32_e32 v80, v11
	v_fma_f32 v11, v91, s80, -v10
	v_fma_f32 v2, v2, s80, -v10
	v_fma_f32 v27, v28, s80, -v26
	v_exp_f32_e32 v81, v11
	v_fma_f32 v11, v92, s80, -v10
	v_exp_f32_e32 v90, v2
	v_fma_f32 v2, v3, s80, -v10
	v_pk_mul_f32 v[20:21], v[54:55], v[14:15] op_sel_hi:[1,0]
	v_exp_f32_e32 v54, v27
	v_fma_f32 v27, v29, s80, -v26
	v_exp_f32_e32 v86, v11
	v_fma_f32 v11, v93, s80, -v10
	v_exp_f32_e32 v91, v2
	v_fma_f32 v2, v4, s80, -v10
	v_exp_f32_e32 v55, v27
	v_fma_f32 v27, v30, s80, -v26
	v_exp_f32_e32 v87, v11
	v_exp_f32_e32 v92, v2
	v_fma_f32 v2, v5, s80, -v10
	v_pk_mul_f32 v[10:11], v[56:57], v[14:15] op_sel_hi:[1,0]
	v_exp_f32_e32 v56, v27
	v_fma_f32 v27, v31, s80, -v26
	v_exp_f32_e32 v57, v27
	v_fma_f32 v27, v68, s80, -v26
	v_pk_mul_f32 v[12:13], v[58:59], v[14:15] op_sel_hi:[1,0]
	v_exp_f32_e32 v58, v27
	v_fma_f32 v27, v69, s80, -v26
	v_exp_f32_e32 v59, v27
	v_fma_f32 v27, v70, s80, -v26
	v_pk_mul_f32 v[22:23], v[60:61], v[14:15] op_sel_hi:[1,0]
	v_sub_f32_e32 v16, v131, v26
	v_exp_f32_e32 v60, v27
	v_fma_f32 v27, v71, s80, -v26
	v_exp_f32_e32 v16, v16
	v_exp_f32_e32 v61, v27
	v_fma_f32 v27, v82, s80, -v26
	v_fma_f32 v6, v6, s80, -v26
	v_pk_mul_f32 v[24:25], v[62:63], v[14:15] op_sel_hi:[1,0]
	v_exp_f32_e32 v62, v27
	v_fma_f32 v27, v83, s80, -v26
	v_exp_f32_e32 v70, v6
	v_fma_f32 v6, v7, s80, -v26
	v_exp_f32_e32 v63, v27
	v_fma_f32 v27, v84, s80, -v26
	v_exp_f32_e32 v71, v6
	v_fma_f32 v6, v8, s80, -v26
	v_exp_f32_e32 v68, v27
	v_fma_f32 v27, v85, s80, -v26
	v_exp_f32_e32 v82, v6
	v_fma_f32 v6, v9, s80, -v26
	v_exp_f32_e32 v93, v2
	v_pk_mul_f32 v[4:5], v[50:51], v[14:15] op_sel_hi:[1,0]
	v_pk_mul_f32 v[2:3], v[48:49], v[14:15] op_sel_hi:[1,0]
	v_pk_mul_f32 v[18:19], v[52:53], v[14:15] op_sel_hi:[1,0]
	v_exp_f32_e32 v69, v27
	v_exp_f32_e32 v83, v6
	v_pk_mul_f32 v[8:9], v[34:35], v[16:17] op_sel_hi:[1,0]
	v_pk_mul_f32 v[6:7], v[32:33], v[16:17] op_sel_hi:[1,0]
	v_pk_mul_f32 v[28:29], v[42:43], v[16:17] op_sel_hi:[1,0]
	v_pk_mul_f32 v[26:27], v[40:41], v[16:17] op_sel_hi:[1,0]
	v_pk_mul_f32 v[32:33], v[38:39], v[16:17] op_sel_hi:[1,0]
	v_pk_mul_f32 v[30:31], v[36:37], v[16:17] op_sel_hi:[1,0]
	v_pk_mul_f32 v[36:37], v[46:47], v[16:17] op_sel_hi:[1,0]
	v_pk_mul_f32 v[34:35], v[44:45], v[16:17] op_sel_hi:[1,0]
	s_setprio 1
	v_add_u32_e32 v1, v1, v123
	ds_read_b128 v[46:49], v1 offset:35840
	v_cvt_pk_bf16_f32 v38, v15, v17
	v_cvt_pk_bf16_f32 v39, v64, v65
	v_cvt_pk_bf16_f32 v40, v66, v67
	v_cvt_pk_bf16_f32 v41, v78, v79
	v_cvt_pk_bf16_f32 v42, v54, v55
	v_cvt_pk_bf16_f32 v43, v56, v57
	v_cvt_pk_bf16_f32 v44, v58, v59
	v_cvt_pk_bf16_f32 v45, v60, v61
	s_waitcnt lgkmcnt(0)
	v_mfma_f32_16x16x32_bf16 v[2:5], v[46:49], v[38:41], v[2:5]
	v_mfma_f32_16x16x32_bf16 v[6:9], v[46:49], v[42:45], v[6:9]
	ds_read_b128 v[46:49], v1 offset:38144
	s_waitcnt lgkmcnt(0)
	v_mfma_f32_16x16x32_bf16 v[10:13], v[46:49], v[38:41], v[10:13]
	v_mfma_f32_16x16x32_bf16 v[26:29], v[46:49], v[42:45], v[26:29]
	ds_read_b128 v[46:49], v1 offset:40448
	s_waitcnt lgkmcnt(0)
	v_mfma_f32_16x16x32_bf16 v[18:21], v[46:49], v[38:41], v[18:21]
	v_mfma_f32_16x16x32_bf16 v[30:33], v[46:49], v[42:45], v[30:33]
	ds_read_b128 v[46:49], v1 offset:42752
	s_waitcnt lgkmcnt(0)
	v_mfma_f32_16x16x32_bf16 v[22:25], v[46:49], v[38:41], v[22:25]
	v_cvt_pk_bf16_f32 v38, v80, v81
	v_cvt_pk_bf16_f32 v39, v86, v87
	v_cvt_pk_bf16_f32 v40, v90, v91
	v_mfma_f32_16x16x32_bf16 v[34:37], v[46:49], v[42:45], v[34:37]
	ds_read_b128 v[46:49], v1 offset:35904
	v_cvt_pk_bf16_f32 v41, v92, v93
	v_cvt_pk_bf16_f32 v42, v62, v63
	v_cvt_pk_bf16_f32 v43, v68, v69
	v_cvt_pk_bf16_f32 v44, v70, v71
	v_cvt_pk_bf16_f32 v45, v82, v83
	s_waitcnt lgkmcnt(0)
	v_mfma_f32_16x16x32_bf16 v[50:53], v[46:49], v[38:41], v[2:5]
	v_mfma_f32_16x16x32_bf16 v[2:5], v[46:49], v[42:45], v[6:9]
	s_nop 2
	ds_read_b128 v[6:9], v1 offset:38208
	s_waitcnt lgkmcnt(0)
; DEVI f32x4 mfma16(bf16x8 a, bf16x8 b, f32x4 c) { return __builtin_amdgcn_mfma_f32_16x16x32_bf16(a, b, c, 0, 0, 0); }
; template <int DQK, int NQ, int MODE, int CH> ...
;     ...
;           for (int md = 0; md < 4; ++md) {
;             const bf16x8 vfr = *reinterpret_cast<const bf16x8*>(Vs + (md * 16 + fr) * VSTR + kc * 32 + fq * 8);
; #pragma unroll
;             for (int nq = 0; nq < NQ; ++nq) o[md][nq] = mfma16(vfr, pf[nq], o[md][nq]);
;           }
;         }
;         __builtin_amdgcn_s_setprio(0);
;       }
;     }
;     if (kt0 + CH < kt_hi) STORE_CHUNK(buf ^ 1);
;     buf ^= 1;
;     __syncthreads();
;   }
;     ...
; #pragma unroll
;   for (int nq = 0; nq < NQ; ++nq) {
;     float l = lsum[nq];
;     l = xor16_sum(l);
;     l = xor32_sum(l);
;     float inv = 1.0f / l;
	v_mfma_f32_16x16x32_bf16 v[46:49], v[6:9], v[38:41], v[10:13]
	s_nop 2
	ds_read_b128 v[10:13], v1 offset:40512
	v_mfma_f32_16x16x32_bf16 v[6:9], v[6:9], v[42:45], v[26:29]
	s_nop 2
	ds_read_b128 v[26:29], v1 offset:42816
	s_waitcnt lgkmcnt(1)
	v_mfma_f32_16x16x32_bf16 v[18:21], v[10:13], v[38:41], v[18:21]
	v_mfma_f32_16x16x32_bf16 v[10:13], v[10:13], v[42:45], v[30:33]
	s_waitcnt lgkmcnt(0)
	v_mfma_f32_16x16x32_bf16 v[22:25], v[26:29], v[38:41], v[22:25]
	v_mfma_f32_16x16x32_bf16 v[26:29], v[26:29], v[42:45], v[34:37]
	s_setprio 0
	v_add_f32_e32 v1, 0, v15
	v_add_f32_e32 v1, v17, v1
	v_add_f32_e32 v1, v64, v1
	v_add_f32_e32 v1, v65, v1
	v_add_f32_e32 v1, v66, v1
	v_add_f32_e32 v1, v67, v1
	v_add_f32_e32 v1, v78, v1
	v_add_f32_e32 v1, v79, v1
	v_add_f32_e32 v1, v80, v1
	v_add_f32_e32 v1, v81, v1
	v_add_f32_e32 v1, v86, v1
	v_add_f32_e32 v1, v87, v1
	v_add_f32_e32 v1, v90, v1
	v_add_f32_e32 v1, v91, v1
	v_add_f32_e32 v1, v92, v1
	v_add_f32_e32 v1, v93, v1
	v_fmac_f32_e32 v1, v76, v14
	v_add_f32_e32 v14, 0, v54
	v_add_f32_e32 v14, v55, v14
	v_add_f32_e32 v14, v56, v14
	v_add_f32_e32 v14, v57, v14
	v_add_f32_e32 v14, v58, v14
	v_add_f32_e32 v14, v59, v14
	v_add_f32_e32 v14, v60, v14
	v_add_f32_e32 v14, v61, v14
	v_add_f32_e32 v14, v62, v14
	v_add_f32_e32 v14, v63, v14
	v_add_f32_e32 v14, v68, v14
	v_add_f32_e32 v14, v69, v14
	v_add_f32_e32 v14, v70, v14
	v_add_f32_e32 v14, v71, v14
	v_add_f32_e32 v14, v82, v14
	v_add_f32_e32 v36, v83, v14
	v_fmac_f32_e32 v36, v77, v16
	v_mov_b32_e32 v16, v1
	s_nop 1
	v_permlane16_swap_b32_e32 v1, v16
	v_add_f32_e32 v1, v1, v16
	v_mov_b32_e32 v16, v1
	s_nop 1
	v_permlane32_swap_b32_e32 v1, v16
	v_lshlrev_b32_e32 v14, 3, v89
	v_mov_b32_e32 v15, v0
	v_add_f32_e32 v1, v1, v16
	v_lshl_add_u64 v[14:15], s[2:3], 0, v[14:15]
	v_div_scale_f32 v16, s[2:3], v1, v1, 1.0
	v_rcp_f32_e32 v17, v16
	s_barrier
; template <int DQK, int NQ, int MODE, int CH> ...
;     ...
; #pragma unroll
;   for (int nq = 0; nq < NQ; ++nq) {
;     float l = lsum[nq];
;     l = xor16_sum(l);
;     l = xor32_sum(l);
;     float inv = 1.0f / l;
;     size_t rowoff = (size_t)(w * 16 * NQ + nq * 16 + fr) * ldo;
; #pragma unroll
;     for (int md = 0; md < 4; ++md) {
;       uint2 ov;
;       ov.x = pack2(o[md][nq][0] * inv, o[md][nq][1] * inv);
;       ov.y = pack2(o[md][nq][2] * inv, o[md][nq][3] * inv);
;       *reinterpret_cast<uint2*>(Op + rowoff + md * 16 + fq * 4) = ov;
;     }
; DEVI void phase3(const Params& p, char* shm) {
;     ...
;       {
;         const int G = (int)gridDim.x;
;         const int j = it / G, nI = (1024 + G - 1) / G;
;         if (j == (int)((blockIdx.x >> 3) % (unsigned)nI)) conv_loop(p, 0, 0, CONV_MOE_JOBS, shm);
	v_fma_f32 v30, -v16, v17, 1.0
	v_fmac_f32_e32 v17, v30, v17
	v_div_scale_f32 v30, vcc, 1.0, v1, 1.0
	v_mul_f32_e32 v31, v30, v17
	v_fma_f32 v32, -v16, v31, v30
	v_fmac_f32_e32 v31, v32, v17
	v_fma_f32 v16, -v16, v31, v30
	v_div_fmas_f32 v16, v16, v17, v31
	v_div_fixup_f32 v16, v16, v1, 1.0
	v_lshlrev_b64 v[30:31], 11, v[74:75]
	v_pk_mul_f32 v[32:33], v[50:51], v[16:17] op_sel_hi:[1,0]
	v_pk_mul_f32 v[34:35], v[52:53], v[16:17] op_sel_hi:[1,0]
	v_pk_mul_f32 v[18:19], v[18:19], v[16:17] op_sel_hi:[1,0]
	v_pk_mul_f32 v[20:21], v[20:21], v[16:17] op_sel_hi:[1,0]
	v_mov_b32_e32 v1, v36
	v_lshl_add_u64 v[30:31], v[14:15], 0, v[30:31]
	v_cvt_pk_bf16_f32 v32, v32, v33
	v_cvt_pk_bf16_f32 v33, v34, v35
	v_cvt_pk_bf16_f32 v18, v18, v19
	v_cvt_pk_bf16_f32 v19, v20, v21
	v_permlane16_swap_b32_e32 v36, v1
	global_store_dwordx2 v[30:31], v[32:33], off offset:1024
	v_pk_mul_f32 v[32:33], v[46:47], v[16:17] op_sel_hi:[1,0]
	v_pk_mul_f32 v[34:35], v[48:49], v[16:17] op_sel_hi:[1,0]
	global_store_dwordx2 v[30:31], v[18:19], off offset:1088
	v_pk_mul_f32 v[18:19], v[22:23], v[16:17] op_sel_hi:[1,0]
	v_pk_mul_f32 v[16:17], v[24:25], v[16:17] op_sel_hi:[1,0]
	v_add_f32_e32 v1, v36, v1
	v_cvt_pk_bf16_f32 v18, v18, v19
	v_cvt_pk_bf16_f32 v19, v16, v17
	v_mov_b32_e32 v16, v1
	s_nop 1
	v_permlane32_swap_b32_e32 v1, v16
	v_add_f32_e32 v1, v1, v16
	v_div_scale_f32 v16, s[2:3], v1, v1, 1.0
	v_rcp_f32_e32 v17, v16
	global_store_dwordx2 v[30:31], v[18:19], off offset:1120
	v_cvt_pk_bf16_f32 v32, v32, v33
	v_cvt_pk_bf16_f32 v33, v34, v35
	v_fma_f32 v18, -v16, v17, 1.0
	v_fmac_f32_e32 v17, v18, v17
	v_div_scale_f32 v18, vcc, 1.0, v1, 1.0
	v_mul_f32_e32 v19, v18, v17
	v_fma_f32 v20, -v16, v19, v18
	v_fmac_f32_e32 v19, v20, v17
	v_fma_f32 v16, -v16, v19, v18
	v_div_fmas_f32 v16, v16, v17, v19
	v_div_fixup_f32 v16, v16, v1, 1.0
	v_lshlrev_b64 v[18:19], 11, v[72:73]
	v_pk_mul_f32 v[2:3], v[2:3], v[16:17] op_sel_hi:[1,0]
	v_pk_mul_f32 v[4:5], v[4:5], v[16:17] op_sel_hi:[1,0]
	v_lshl_add_u64 v[14:15], v[14:15], 0, v[18:19]
	v_cvt_pk_bf16_f32 v2, v2, v3
	v_cvt_pk_bf16_f32 v3, v4, v5
	global_store_dwordx2 v[14:15], v[2:3], off offset:1024
	v_pk_mul_f32 v[2:3], v[6:7], v[16:17] op_sel_hi:[1,0]
	v_pk_mul_f32 v[4:5], v[8:9], v[16:17] op_sel_hi:[1,0]
	v_cvt_pk_bf16_f32 v2, v2, v3
	v_cvt_pk_bf16_f32 v3, v4, v5
	global_store_dwordx2 v[14:15], v[2:3], off offset:1056
	v_pk_mul_f32 v[2:3], v[10:11], v[16:17] op_sel_hi:[1,0]
	v_pk_mul_f32 v[4:5], v[12:13], v[16:17] op_sel_hi:[1,0]
	v_cvt_pk_bf16_f32 v2, v2, v3
	v_cvt_pk_bf16_f32 v3, v4, v5
	global_store_dwordx2 v[14:15], v[2:3], off offset:1088
	v_pk_mul_f32 v[2:3], v[26:27], v[16:17] op_sel_hi:[1,0]
	v_pk_mul_f32 v[4:5], v[28:29], v[16:17] op_sel_hi:[1,0]
	v_cvt_pk_bf16_f32 v2, v2, v3
	v_cvt_pk_bf16_f32 v3, v4, v5
	global_store_dwordx2 v[30:31], v[32:33], off offset:1056
	global_store_dwordx2 v[14:15], v[2:3], off offset:1120
	s_load_dword s0, s[42:43], 0x10
	s_waitcnt lgkmcnt(0)
	s_lshr_b32 s0, s0, 16
	s_cmp_lg_u32 s0, 0
	s_cselect_b64 s[2:3], -1, 0
	s_cmp_lg_u64 s[2:3], 0
	s_addc_u32 s61, s78, 0
	s_abs_i32 s4, s61
	v_cvt_f32_u32_e32 v1, s4
	s_sub_i32 s5, 0, s4
	s_abs_i32 s3, s82
	s_ashr_i32 s0, s82, 31
	v_rcp_iflag_f32_e32 v1, v1
	s_ashr_i32 s2, s61, 31
	s_xor_b32 s0, s0, s2
	v_mul_f32_e32 v1, 0x4f7ffffe, v1
	v_cvt_u32_f32_e32 v1, v1
	s_nop 0
	v_readfirstlane_b32 s21, v1
	s_mul_i32 s5, s5, s21
	s_mul_hi_u32 s5, s21, s5
	s_add_i32 s21, s21, s5
	s_mul_hi_u32 s5, s3, s21
	s_mul_i32 s28, s5, s4
	s_sub_i32 s3, s3, s28
	s_add_i32 s28, s5, 1
	s_sub_i32 s29, s3, s4
	s_cmp_ge_u32 s3, s4
	s_cselect_b32 s5, s28, s5
	s_cselect_b32 s3, s29, s3
	s_add_i32 s28, s5, 1
	s_cmp_ge_u32 s3, s4
	s_cselect_b32 s3, s28, s5
	s_xor_b32 s3, s3, s0
	s_sub_i32 s0, s3, s0
	s_add_i32 s3, s61, 0x3ff
	s_ashr_i32 s5, s3, 31
	s_abs_i32 s3, s3
	s_xor_b32 s2, s5, s2
	s_mul_hi_u32 s5, s3, s21
	s_mul_i32 s21, s5, s4
	s_sub_i32 s3, s3, s21
	s_add_i32 s21, s5, 1
	s_sub_i32 s28, s3, s4
	s_cmp_ge_u32 s3, s4
	s_cselect_b32 s5, s21, s5
	s_cselect_b32 s3, s28, s3
	s_add_i32 s21, s5, 1
	s_cmp_ge_u32 s3, s4
	s_cselect_b32 s3, s21, s5
	s_xor_b32 s3, s3, s2
	s_sub_i32 s2, s3, s2
	v_cvt_f32_u32_e32 v1, s2
	s_sub_i32 s3, 0, s2
	v_rcp_iflag_f32_e32 v1, v1
	s_nop 0
	v_mul_f32_e32 v1, 0x4f7ffffe, v1
	v_cvt_u32_f32_e32 v1, v1
	s_nop 0
	v_readfirstlane_b32 s4, v1
	s_mul_i32 s3, s3, s4
	s_mul_hi_u32 s3, s4, s3
	s_add_i32 s4, s4, s3
	s_mul_hi_u32 s3, s33, s4
	s_mul_i32 s3, s3, s2
	s_sub_i32 s3, s33, s3
	s_sub_i32 s4, s3, s2
	s_cmp_ge_u32 s3, s2
	s_cselect_b32 s3, s4, s3
	s_sub_i32 s4, s3, s2
	s_cmp_ge_u32 s3, s2
	s_cselect_b32 s2, s4, s3
	s_cmp_lg_u32 s0, s2
	s_cbranch_scc1 .LBB0_807
	v_mov_b32_e32 v36, v214
	v_readlane_b32 s2, v241, 14
	v_lshlrev_b32_e32 v1, 2, v36
	v_and_b32_e32 v41, 60, v1
	v_or_b32_e32 v1, s11, v41
	v_ashrrev_i32_e32 v40, 4, v36
	v_lshlrev_b32_e32 v2, 2, v1
	v_mov_b32_e32 v3, v0
	v_readlane_b32 s3, v241, 15
	v_mov_b32_e32 v6, v0
	v_mov_b32_e32 v7, v0
	v_cmp_gt_u32_e32 vcc, s81, v1
	v_add_u32_e32 v18, s10, v40
	v_lshl_add_u64 v[20:21], s[2:3], 0, v[2:3]
	v_mov_b64_e32 v[2:3], v[6:7]
	v_mov_b64_e32 v[4:5], v[6:7]
	s_and_saveexec_b64 s[2:3], vcc
	s_cbranch_execz .LBB0_840
	v_ashrrev_i32_e32 v19, 31, v18
	v_lshlrev_b64 v[2:3], s65, v[18:19]
	v_lshl_add_u64 v[2:3], v[2:3], 2, v[20:21]
	global_load_dwordx4 v[2:5], v[2:3], off
